# attention work queue: next unit index claimed by an atomic issued during the last K/V step of the current unit (hides the dequeue round trip), on top of the rewritten FFN-up epilogue
# speedup vs baseline: 1.0077x; 1.0077x over previous
; #define LAS __attribute__((address_space(3)))
; __global__ void __launch_bounds__(NTHREADS, 2) mega_fwd(Args args) {
;     ...
;                     AttnP P{QKB, VT, OB, FG, args.in[2] + l * 6, args.in[7] + l * 64, (const float*)ctl + 1024 + l, args.lam_init[l]};
;                     volatile LAS unsigned* nxt = (volatile LAS unsigned*)(lds + MISC_OFF);
;     ...
;                   for (int rep = 0; rep < 2; ++rep) { if (rep) { xcd_barrier(xbar); if (bx == 0 && tid == 0) ctl[64 * l] = 0u; xcd_barrier(xbar); }
;     ...
;                     const int xq = bx & 7;
;                     for (;;) {
;                         if (tid == 0) nxt[0] = atomicAdd(ctl + 64 * l + 8 * (xq + 1), 1u);
;                         __syncthreads();
;                         const unsigned u = nxt[0];
;                         __syncthreads();
;                         if (u >= 256u) break;
.LBB0_620:
	s_or_b64 exec, exec, s[0:1]
	v_readlane_b32 s0, v251, 11
	v_readlane_b32 s1, v251, 12
	s_waitcnt lgkmcnt(0)
	s_barrier
	s_load_dword s0, s[0:1], 0xa8
	s_waitcnt lgkmcnt(0)
	v_sub_f32_e64 v212, 1.0, s0
	v_mov_b32_e32 v255, -1
	s_branch .LBB0_623
.Lclaim_fox:
	s_mov_b64 s[96:97], exec
	v_readlane_b32 s94, v252, 10
	v_readlane_b32 s95, v252, 11
	s_and_b64 s[94:95], s[96:97], s[94:95]
	s_mov_b64 exec, s[94:95]
	s_cbranch_execz .Lclaim_fox_done
	v_readlane_b32 s94, v251, 13
	v_readlane_b32 s95, v251, 14
	s_nop 4
	global_atomic_add v255, v1, v242, s[94:95] offset:32 sc0
.Lclaim_fox_done:
	s_mov_b64 exec, s[96:97]
	s_branch .LBB0_664

; __global__ void __launch_bounds__(NTHREADS, 2) mega_fwd(Args args) {
;     ...
;                     for (;;) {
;                         if (tid == 0) nxt[0] = atomicAdd(ctl + 64 * l + 8 * (xq + 1), 1u);
;                         __syncthreads();
;                         const unsigned u = nxt[0];
;                         __syncthreads();
;                         if (u >= 256u) break;
;                         const int jj = (int)(u & 63u), qb = 15 - (jj >> 2), rem = xq + 8 * (4 * (int)(u >> 6) + (jj & 3));
.LBB0_623:
	s_mov_b64 s[0:1], exec
	v_readlane_b32 s2, v252, 10
	v_readlane_b32 s3, v252, 11
	s_and_b64 s[2:3], s[0:1], s[2:3]
	s_mov_b64 exec, s[2:3]
	s_cbranch_execz .LBB0_627
	s_waitcnt vmcnt(0)
	v_cmp_ne_u32_e32 vcc, -1, v255
	s_cbranch_vccnz .Lhave_claim
	v_readlane_b32 s2, v251, 13
	v_readlane_b32 s3, v251, 14
	s_nop 4
	global_atomic_add v255, v1, v242, s[2:3] offset:32 sc0
	s_waitcnt vmcnt(0)
.Lhave_claim:
	v_mov_b32_e32 v0, v255
	v_mov_b32_e32 v255, -1
	v_readlane_b32 s2, v252, 7
	s_nop 1
	v_mov_b32_e32 v2, s2
	ds_write_b32 v2, v0

; #define ATT_GLOAD(dst, ptr) asm volatile("global_load_dwordx4 %0, %1, off" : "+v"(dst) : "v"(ptr) : "memory")
; template <int MODE> __device__ __forceinline__ void attn_unit(LAS unsigned char* lds, const AttnP& P, int b, int h, int qb) {
;     ...
;         const int buf = (T - T_lo) & 1; const bool more = T < T_hi;
;         if (more) { const bf16_t* kp = kg + (size_t)((T + 1) * 128) * NQK; const bf16_t* vp = vg + (T + 1) * 128;
;             ATT_GLOAD(ka, kp); ATT_GLOAD(kb2, kp + (size_t)64 * NQK); ATT_GLOAD(va, vp); ATT_GLOAD(vb2, vp + 64); }
;         compute(2 * T, buf * KSTEP, buf * VSTEP);
.Lclaim_diff_done:
	s_mov_b64 exec, s[96:97]
	s_and_b32 s33, s16, 1
	s_cmp_gt_i32 s27, s39
	s_mul_i32 s2, s33, 0x4800
	s_cbranch_scc0 .LBB0_804

; __global__ void __launch_bounds__(NTHREADS, 2) mega_fwd(Args args) {
	.amdhsa_kernel _Z8mega_fwd4Args
		.amdhsa_group_segment_fixed_size 0
		.amdhsa_private_segment_fixed_size 0
		.amdhsa_kernarg_size 440
		.amdhsa_user_sgpr_count 2
		.amdhsa_user_sgpr_dispatch_ptr 0
		.amdhsa_user_sgpr_queue_ptr 0
		.amdhsa_user_sgpr_kernarg_segment_ptr 1
		.amdhsa_user_sgpr_dispatch_id 0
		.amdhsa_user_sgpr_kernarg_preload_length 0
		.amdhsa_user_sgpr_kernarg_preload_offset 0
		.amdhsa_user_sgpr_private_segment_size 0
		.amdhsa_uses_dynamic_stack 0
		.amdhsa_enable_private_segment 0
		.amdhsa_system_sgpr_workgroup_id_x 1
		.amdhsa_system_sgpr_workgroup_id_y 0
		.amdhsa_system_sgpr_workgroup_id_z 0
		.amdhsa_system_sgpr_workgroup_info 0
		.amdhsa_system_vgpr_workitem_id 2
		.amdhsa_next_free_vgpr 256
		.amdhsa_next_free_sgpr 98
		.amdhsa_accum_offset 256
		.amdhsa_reserve_vcc 1
		.amdhsa_float_round_mode_32 0
		.amdhsa_float_round_mode_16_64 0
		.amdhsa_float_denorm_mode_32 3
		.amdhsa_float_denorm_mode_16_64 3
		.amdhsa_dx10_clamp 1
		.amdhsa_ieee_mode 1
		.amdhsa_fp16_overflow 0
		.amdhsa_tg_split 0
		.amdhsa_exception_fp_ieee_invalid_op 0
		.amdhsa_exception_fp_denorm_src 0
		.amdhsa_exception_fp_ieee_div_zero 0
		.amdhsa_exception_fp_ieee_overflow 0
		.amdhsa_exception_fp_ieee_underflow 0
		.amdhsa_exception_fp_ieee_inexact 0
		.amdhsa_exception_int_div_zero 0
	.end_amdhsa_kernel

; __global__ void __launch_bounds__(NTHREADS, 2) mega_fwd(Args args) {
amdhsa.kernels:
  - .agpr_count:     0
    .args:
      - .offset:         0
        .size:           184
        .value_kind:     by_value
      - .offset:         184
        .size:           4
        .value_kind:     hidden_block_count_x
      - .offset:         188
        .size:           4
        .value_kind:     hidden_block_count_y
      - .offset:         192
        .size:           4
        .value_kind:     hidden_block_count_z
      - .offset:         196
        .size:           2
        .value_kind:     hidden_group_size_x
      - .offset:         198
        .size:           2
        .value_kind:     hidden_group_size_y
      - .offset:         200
        .size:           2
        .value_kind:     hidden_group_size_z
      - .offset:         202
        .size:           2
        .value_kind:     hidden_remainder_x
      - .offset:         204
        .size:           2
        .value_kind:     hidden_remainder_y
      - .offset:         206
        .size:           2
        .value_kind:     hidden_remainder_z
      - .offset:         224
        .size:           8
        .value_kind:     hidden_global_offset_x
      - .offset:         232
        .size:           8
        .value_kind:     hidden_global_offset_y
      - .offset:         240
        .size:           8
        .value_kind:     hidden_global_offset_z
      - .offset:         248
        .size:           2
        .value_kind:     hidden_grid_dims
      - .offset:         272
        .size:           8
        .value_kind:     hidden_multigrid_sync_arg
      - .offset:         304
        .size:           4
        .value_kind:     hidden_dynamic_lds_size
    .group_segment_fixed_size: 0
    .kernarg_segment_align: 8
    .kernarg_segment_size: 440
    .language:       OpenCL C
    .language_version:
      - 2
      - 0
    .max_flat_workgroup_size: 512
    .name:           _Z8mega_fwd4Args
    .private_segment_fixed_size: 0
    .sgpr_count:     104
    .sgpr_spill_count: 255
    .symbol:         _Z8mega_fwd4Args.kd
    .uniform_work_group_size: 1
    .uses_dynamic_stack: false
    .vgpr_count:     256
    .vgpr_spill_count: 0
    .wavefront_size: 64
